# x18 + removed the dead shuffle-address VALU code in front of 16 permlane32 swaps in the GIN epilogue
# baseline (speedup 1.0000x reference)
; __device__ __forceinline__ float dot4(const f32x4& v) { return (v[0] * v[0] + v[1] * v[1]) + (v[2] * v[2] + v[3] * v[3]); }
;     __device__ __forceinline__ void operator()(const f32x4 (&acc)[2][2][4][2], const Unit& u, int wr, int wc, int fr, int fq) const {
;     ...
;                         if (colw >= ZCQ && colw < ZKR) { float sb = dot4(v0) + dot4(v1); sb += __shfl_xor(sb, 16); sb += __shfl_xor(sb, 32);
;                             if (fq == 0) rstat[(size_t)row * 16 + ((colw - ZCQ) >> 5)] = sb; }
.LBB0_389:
	s_andn2_b64 vcc, exec, s[42:43]
	s_cbranch_vccnz .LBB0_393
	v_mul_f32_e32 v147, v127, v127
	v_mul_f32_e32 v150, v129, v129
	v_fmac_f32_e32 v147, v126, v126
	v_fmac_f32_e32 v150, v128, v128
	v_add_f32_e32 v147, v147, v150
	v_mul_f32_e32 v150, v123, v123
	v_mul_f32_e32 v151, v125, v125
	v_fmac_f32_e32 v150, v122, v122
	v_fmac_f32_e32 v151, v124, v124
	v_add_f32_e32 v150, v150, v151
	v_and_b32_e32 v151, 64, v215
	v_add_f32_e32 v147, v150, v147
	v_xor_b32_e32 v150, 16, v215
	v_add_u32_e32 v151, 64, v151
	v_cmp_lt_i32_e32 vcc, v150, v151
	s_nop 1
	v_cndmask_b32_e32 v150, v215, v150, vcc
	v_lshlrev_b32_e32 v150, 2, v150
	v_mov_b32_e32 v150, v147
	s_nop 1
	v_permlane16_swap_b32_e32 v150, v147
	s_waitcnt lgkmcnt(0)
	v_add_f32_e32 v147, v147, v150
	v_mov_b32_e32 v150, v147
	s_nop 1
	v_permlane32_swap_b32_e32 v150, v147
	s_and_saveexec_b64 s[42:43], s[38:39]
	s_cbranch_execz .LBB0_392
	v_lshl_add_u64 v[152:153], s[50:51], 0, v[148:149]
	s_lshr_b32 s76, s19, 3
	v_lshl_add_u64 v[152:153], v[152:153], 0, s[76:77]
	s_waitcnt lgkmcnt(0)
	v_add_f32_e32 v147, v147, v150
	global_store_dword v[152:153], v147, off

; __device__ __forceinline__ float dot4(const f32x4& v) { return (v[0] * v[0] + v[1] * v[1]) + (v[2] * v[2] + v[3] * v[3]); }
;     __device__ __forceinline__ void operator()(const f32x4 (&acc)[2][2][4][2], const Unit& u, int wr, int wc, int fr, int fq) const {
;     ...
;                         if (colw >= ZCQ && colw < ZKR) { float sb = dot4(v0) + dot4(v1); sb += __shfl_xor(sb, 16); sb += __shfl_xor(sb, 32);
;                             if (fq == 0) rstat[(size_t)row * 16 + ((colw - ZCQ) >> 5)] = sb; }
.LBB0_399:
	s_andn2_b64 vcc, exec, s[66:67]
	s_cbranch_vccnz .LBB0_403
	v_mul_f32_e32 v122, v119, v119
	v_mul_f32_e32 v123, v121, v121
	v_fmac_f32_e32 v122, v118, v118
	v_fmac_f32_e32 v123, v120, v120
	v_add_f32_e32 v122, v122, v123
	v_mul_f32_e32 v123, v115, v115
	v_mul_f32_e32 v124, v117, v117
	v_fmac_f32_e32 v123, v114, v114
	v_fmac_f32_e32 v124, v116, v116
	v_add_f32_e32 v123, v123, v124
	v_and_b32_e32 v124, 64, v215
	v_add_f32_e32 v122, v123, v122
	v_xor_b32_e32 v123, 16, v215
	v_add_u32_e32 v124, 64, v124
	v_cmp_lt_i32_e32 vcc, v123, v124
	s_nop 1
	v_cndmask_b32_e32 v123, v215, v123, vcc
	v_lshlrev_b32_e32 v123, 2, v123
	v_mov_b32_e32 v123, v122
	s_nop 1
	v_permlane16_swap_b32_e32 v123, v122
	s_waitcnt lgkmcnt(0)
	v_add_f32_e32 v122, v122, v123
	v_mov_b32_e32 v123, v122
	s_nop 1
	v_permlane32_swap_b32_e32 v123, v122
	s_and_saveexec_b64 s[66:67], s[38:39]
	s_cbranch_execz .LBB0_402
	v_lshl_add_u64 v[124:125], s[50:51], 0, v[148:149]
	s_lshr_b32 s76, s19, 3
	v_lshl_add_u64 v[124:125], v[124:125], 0, s[76:77]
	s_waitcnt lgkmcnt(0)
	v_add_f32_e32 v122, v122, v123
	global_store_dword v[124:125], v122, off

; __device__ __forceinline__ float dot4(const f32x4& v) { return (v[0] * v[0] + v[1] * v[1]) + (v[2] * v[2] + v[3] * v[3]); }
;     __device__ __forceinline__ void operator()(const f32x4 (&acc)[2][2][4][2], const Unit& u, int wr, int wc, int fr, int fq) const {
;     ...
;                         if (colw >= ZCQ && colw < ZKR) { float sb = dot4(v0) + dot4(v1); sb += __shfl_xor(sb, 16); sb += __shfl_xor(sb, 32);
;                             if (fq == 0) rstat[(size_t)row * 16 + ((colw - ZCQ) >> 5)] = sb; }
.LBB0_409:
	s_andn2_b64 vcc, exec, s[66:67]
	s_cbranch_vccnz .LBB0_413
	v_mul_f32_e32 v117, v111, v111
	v_mul_f32_e32 v118, v113, v113
	v_fmac_f32_e32 v117, v110, v110
	v_fmac_f32_e32 v118, v112, v112
	v_add_f32_e32 v117, v117, v118
	v_mul_f32_e32 v118, v107, v107
	v_mul_f32_e32 v119, v109, v109
	v_fmac_f32_e32 v118, v106, v106
	v_fmac_f32_e32 v119, v108, v108
	v_add_f32_e32 v118, v118, v119
	v_and_b32_e32 v119, 64, v215
	v_add_f32_e32 v117, v118, v117
	v_xor_b32_e32 v118, 16, v215
	v_add_u32_e32 v119, 64, v119
	v_cmp_lt_i32_e32 vcc, v118, v119
	s_nop 1
	v_cndmask_b32_e32 v118, v215, v118, vcc
	v_lshlrev_b32_e32 v118, 2, v118
	v_mov_b32_e32 v118, v117
	s_nop 1
	v_permlane16_swap_b32_e32 v118, v117
	s_waitcnt lgkmcnt(0)
	v_add_f32_e32 v117, v117, v118
	v_mov_b32_e32 v118, v117
	s_nop 1
	v_permlane32_swap_b32_e32 v118, v117
	s_and_saveexec_b64 s[66:67], s[38:39]
	s_cbranch_execz .LBB0_412
	v_lshl_add_u64 v[120:121], s[50:51], 0, v[114:115]
	s_lshr_b32 s76, s19, 3
	v_lshl_add_u64 v[120:121], v[120:121], 0, s[76:77]
	s_waitcnt lgkmcnt(0)
	v_add_f32_e32 v117, v117, v118
	global_store_dword v[120:121], v117, off

; __device__ __forceinline__ float dot4(const f32x4& v) { return (v[0] * v[0] + v[1] * v[1]) + (v[2] * v[2] + v[3] * v[3]); }
;     __device__ __forceinline__ void operator()(const f32x4 (&acc)[2][2][4][2], const Unit& u, int wr, int wc, int fr, int fq) const {
;     ...
;                         if (colw >= ZCQ && colw < ZKR) { float sb = dot4(v0) + dot4(v1); sb += __shfl_xor(sb, 16); sb += __shfl_xor(sb, 32);
;                             if (fq == 0) rstat[(size_t)row * 16 + ((colw - ZCQ) >> 5)] = sb; }
.LBB0_419:
	s_andn2_b64 vcc, exec, s[66:67]
	s_cbranch_vccnz .LBB0_423
	v_mul_f32_e32 v106, v103, v103
	v_mul_f32_e32 v107, v105, v105
	v_fmac_f32_e32 v106, v102, v102
	v_fmac_f32_e32 v107, v104, v104
	v_add_f32_e32 v106, v106, v107
	v_mul_f32_e32 v107, v99, v99
	v_mul_f32_e32 v108, v101, v101
	v_fmac_f32_e32 v107, v98, v98
	v_fmac_f32_e32 v108, v100, v100
	v_add_f32_e32 v107, v107, v108
	v_and_b32_e32 v108, 64, v215
	v_add_f32_e32 v106, v107, v106
	v_xor_b32_e32 v107, 16, v215
	v_add_u32_e32 v108, 64, v108
	v_cmp_lt_i32_e32 vcc, v107, v108
	s_nop 1
	v_cndmask_b32_e32 v107, v215, v107, vcc
	v_lshlrev_b32_e32 v107, 2, v107
	v_mov_b32_e32 v107, v106
	s_nop 1
	v_permlane16_swap_b32_e32 v107, v106
	s_waitcnt lgkmcnt(0)
	v_add_f32_e32 v106, v106, v107
	v_mov_b32_e32 v107, v106
	s_nop 1
	v_permlane32_swap_b32_e32 v107, v106
	s_and_saveexec_b64 s[66:67], s[38:39]
	s_cbranch_execz .LBB0_422
	v_lshl_add_u64 v[108:109], s[50:51], 0, v[114:115]
	s_lshr_b32 s76, s19, 3
	v_lshl_add_u64 v[108:109], v[108:109], 0, s[76:77]
	s_waitcnt lgkmcnt(0)
	v_add_f32_e32 v106, v106, v107
	global_store_dword v[108:109], v106, off

; __device__ __forceinline__ float dot4(const f32x4& v) { return (v[0] * v[0] + v[1] * v[1]) + (v[2] * v[2] + v[3] * v[3]); }
;     __device__ __forceinline__ void operator()(const f32x4 (&acc)[2][2][4][2], const Unit& u, int wr, int wc, int fr, int fq) const {
;     ...
;                         if (colw >= ZCQ && colw < ZKR) { float sb = dot4(v0) + dot4(v1); sb += __shfl_xor(sb, 16); sb += __shfl_xor(sb, 32);
;                             if (fq == 0) rstat[(size_t)row * 16 + ((colw - ZCQ) >> 5)] = sb; }
.LBB0_429:
	s_andn2_b64 vcc, exec, s[66:67]
	s_cbranch_vccnz .LBB0_433
	v_mul_f32_e32 v101, v93, v93
	v_mul_f32_e32 v102, v95, v95
	v_fmac_f32_e32 v101, v92, v92
	v_fmac_f32_e32 v102, v94, v94
	v_add_f32_e32 v101, v101, v102
	v_mul_f32_e32 v102, v89, v89
	v_mul_f32_e32 v103, v91, v91
	v_fmac_f32_e32 v102, v88, v88
	v_fmac_f32_e32 v103, v90, v90
	v_add_f32_e32 v102, v102, v103
	v_and_b32_e32 v103, 64, v215
	v_add_f32_e32 v101, v102, v101
	v_xor_b32_e32 v102, 16, v215
	v_add_u32_e32 v103, 64, v103
	v_cmp_lt_i32_e32 vcc, v102, v103
	s_nop 1
	v_cndmask_b32_e32 v102, v215, v102, vcc
	v_lshlrev_b32_e32 v102, 2, v102
	v_mov_b32_e32 v102, v101
	s_nop 1
	v_permlane16_swap_b32_e32 v102, v101
	s_waitcnt lgkmcnt(0)
	v_add_f32_e32 v101, v101, v102
	v_mov_b32_e32 v102, v101
	s_nop 1
	v_permlane32_swap_b32_e32 v102, v101
	s_and_saveexec_b64 s[66:67], s[38:39]
	s_cbranch_execz .LBB0_432
	v_lshl_add_u64 v[104:105], s[50:51], 0, v[98:99]
	s_lshr_b32 s76, s19, 3
	v_lshl_add_u64 v[104:105], v[104:105], 0, s[76:77]
	s_waitcnt lgkmcnt(0)
	v_add_f32_e32 v101, v101, v102
	global_store_dword v[104:105], v101, off

; __device__ __forceinline__ float dot4(const f32x4& v) { return (v[0] * v[0] + v[1] * v[1]) + (v[2] * v[2] + v[3] * v[3]); }
;     __device__ __forceinline__ void operator()(const f32x4 (&acc)[2][2][4][2], const Unit& u, int wr, int wc, int fr, int fq) const {
;     ...
;                         if (colw >= ZCQ && colw < ZKR) { float sb = dot4(v0) + dot4(v1); sb += __shfl_xor(sb, 16); sb += __shfl_xor(sb, 32);
;                             if (fq == 0) rstat[(size_t)row * 16 + ((colw - ZCQ) >> 5)] = sb; }
.LBB0_439:
	s_andn2_b64 vcc, exec, s[66:67]
	s_cbranch_vccnz .LBB0_443
	v_mul_f32_e32 v88, v85, v85
	v_mul_f32_e32 v89, v87, v87
	v_fmac_f32_e32 v88, v84, v84
	v_fmac_f32_e32 v89, v86, v86
	v_add_f32_e32 v88, v88, v89
	v_mul_f32_e32 v89, v81, v81
	v_mul_f32_e32 v90, v83, v83
	v_fmac_f32_e32 v89, v80, v80
	v_fmac_f32_e32 v90, v82, v82
	v_add_f32_e32 v89, v89, v90
	v_and_b32_e32 v90, 64, v215
	v_add_f32_e32 v88, v89, v88
	v_xor_b32_e32 v89, 16, v215
	v_add_u32_e32 v90, 64, v90
	v_cmp_lt_i32_e32 vcc, v89, v90
	s_nop 1
	v_cndmask_b32_e32 v89, v215, v89, vcc
	v_lshlrev_b32_e32 v89, 2, v89
	v_mov_b32_e32 v89, v88
	s_nop 1
	v_permlane16_swap_b32_e32 v89, v88
	s_waitcnt lgkmcnt(0)
	v_add_f32_e32 v88, v88, v89
	v_mov_b32_e32 v89, v88
	s_nop 1
	v_permlane32_swap_b32_e32 v89, v88
	s_and_saveexec_b64 s[66:67], s[38:39]
	s_cbranch_execz .LBB0_442
	v_lshl_add_u64 v[90:91], s[50:51], 0, v[98:99]
	s_lshr_b32 s76, s19, 3
	v_lshl_add_u64 v[90:91], v[90:91], 0, s[76:77]
	s_waitcnt lgkmcnt(0)
	v_add_f32_e32 v88, v88, v89
	global_store_dword v[90:91], v88, off

; __device__ __forceinline__ float dot4(const f32x4& v) { return (v[0] * v[0] + v[1] * v[1]) + (v[2] * v[2] + v[3] * v[3]); }
;     __device__ __forceinline__ void operator()(const f32x4 (&acc)[2][2][4][2], const Unit& u, int wr, int wc, int fr, int fq) const {
;     ...
;                         if (colw >= ZCQ && colw < ZKR) { float sb = dot4(v0) + dot4(v1); sb += __shfl_xor(sb, 16); sb += __shfl_xor(sb, 32);
;                             if (fq == 0) rstat[(size_t)row * 16 + ((colw - ZCQ) >> 5)] = sb; }
.LBB0_449:
	s_andn2_b64 vcc, exec, s[66:67]
	s_cbranch_vccnz .LBB0_453
	v_mul_f32_e32 v83, v77, v77
	v_mul_f32_e32 v84, v79, v79
	v_fmac_f32_e32 v83, v76, v76
	v_fmac_f32_e32 v84, v78, v78
	v_add_f32_e32 v83, v83, v84
	v_mul_f32_e32 v84, v73, v73
	v_mul_f32_e32 v85, v75, v75
	v_fmac_f32_e32 v84, v72, v72
	v_fmac_f32_e32 v85, v74, v74
	v_add_f32_e32 v84, v84, v85
	v_and_b32_e32 v85, 64, v215
	v_add_f32_e32 v83, v84, v83
	v_xor_b32_e32 v84, 16, v215
	v_add_u32_e32 v85, 64, v85
	v_cmp_lt_i32_e32 vcc, v84, v85
	s_nop 1
	v_cndmask_b32_e32 v84, v215, v84, vcc
	v_lshlrev_b32_e32 v84, 2, v84
	v_mov_b32_e32 v84, v83
	s_nop 1
	v_permlane16_swap_b32_e32 v84, v83
	s_waitcnt lgkmcnt(0)
	v_add_f32_e32 v83, v83, v84
	v_mov_b32_e32 v84, v83
	s_nop 1
	v_permlane32_swap_b32_e32 v84, v83
	s_and_saveexec_b64 s[66:67], s[38:39]
	s_cbranch_execz .LBB0_452
	v_lshl_add_u64 v[86:87], s[50:51], 0, v[80:81]
	s_lshr_b32 s76, s19, 3
	v_lshl_add_u64 v[86:87], v[86:87], 0, s[76:77]
	s_waitcnt lgkmcnt(0)
	v_add_f32_e32 v83, v83, v84
	global_store_dword v[86:87], v83, off

; __device__ __forceinline__ float dot4(const f32x4& v) { return (v[0] * v[0] + v[1] * v[1]) + (v[2] * v[2] + v[3] * v[3]); }
;     __device__ __forceinline__ void operator()(const f32x4 (&acc)[2][2][4][2], const Unit& u, int wr, int wc, int fr, int fq) const {
;     ...
;                         if (colw >= ZCQ && colw < ZKR) { float sb = dot4(v0) + dot4(v1); sb += __shfl_xor(sb, 16); sb += __shfl_xor(sb, 32);
;                             if (fq == 0) rstat[(size_t)row * 16 + ((colw - ZCQ) >> 5)] = sb; }
.LBB0_459:
	s_andn2_b64 vcc, exec, s[66:67]
	s_cbranch_vccnz .LBB0_463
	v_mul_f32_e32 v72, v69, v69
	v_mul_f32_e32 v73, v71, v71
	v_fmac_f32_e32 v72, v68, v68
	v_fmac_f32_e32 v73, v70, v70
	v_add_f32_e32 v72, v72, v73
	v_mul_f32_e32 v73, v65, v65
	v_mul_f32_e32 v74, v67, v67
	v_fmac_f32_e32 v73, v64, v64
	v_fmac_f32_e32 v74, v66, v66
	v_add_f32_e32 v73, v73, v74
	v_and_b32_e32 v74, 64, v215
	v_add_f32_e32 v72, v73, v72
	v_xor_b32_e32 v73, 16, v215
	v_add_u32_e32 v74, 64, v74
	v_cmp_lt_i32_e32 vcc, v73, v74
	s_nop 1
	v_cndmask_b32_e32 v73, v215, v73, vcc
	v_lshlrev_b32_e32 v73, 2, v73
	v_mov_b32_e32 v73, v72
	s_nop 1
	v_permlane16_swap_b32_e32 v73, v72
	s_waitcnt lgkmcnt(0)
	v_add_f32_e32 v72, v72, v73
	v_mov_b32_e32 v73, v72
	s_nop 1
	v_permlane32_swap_b32_e32 v73, v72
	s_and_saveexec_b64 s[66:67], s[38:39]
	s_cbranch_execz .LBB0_462
	v_lshl_add_u64 v[74:75], s[50:51], 0, v[80:81]
	s_lshr_b32 s76, s18, 3
	v_lshl_add_u64 v[74:75], v[74:75], 0, s[76:77]
	s_waitcnt lgkmcnt(0)
	v_add_f32_e32 v72, v72, v73
	global_store_dword v[74:75], v72, off

; __device__ __forceinline__ float dot4(const f32x4& v) { return (v[0] * v[0] + v[1] * v[1]) + (v[2] * v[2] + v[3] * v[3]); }
;     __device__ __forceinline__ void operator()(const f32x4 (&acc)[2][2][4][2], const Unit& u, int wr, int wc, int fr, int fq) const {
;     ...
;                         if (colw >= ZCQ && colw < ZKR) { float sb = dot4(v0) + dot4(v1); sb += __shfl_xor(sb, 16); sb += __shfl_xor(sb, 32);
;                             if (fq == 0) rstat[(size_t)row * 16 + ((colw - ZCQ) >> 5)] = sb; }
.LBB0_469:
	s_andn2_b64 vcc, exec, s[66:67]
	s_cbranch_vccnz .LBB0_473
	v_mul_f32_e32 v67, v61, v61
	v_mul_f32_e32 v68, v63, v63
	v_fmac_f32_e32 v67, v60, v60
	v_fmac_f32_e32 v68, v62, v62
	v_add_f32_e32 v67, v67, v68
	v_mul_f32_e32 v68, v57, v57
	v_mul_f32_e32 v69, v59, v59
	v_fmac_f32_e32 v68, v56, v56
	v_fmac_f32_e32 v69, v58, v58
	v_add_f32_e32 v68, v68, v69
	v_and_b32_e32 v69, 64, v215
	v_add_f32_e32 v67, v68, v67
	v_xor_b32_e32 v68, 16, v215
	v_add_u32_e32 v69, 64, v69
	v_cmp_lt_i32_e32 vcc, v68, v69
	s_nop 1
	v_cndmask_b32_e32 v68, v215, v68, vcc
	v_lshlrev_b32_e32 v68, 2, v68
	v_mov_b32_e32 v68, v67
	s_nop 1
	v_permlane16_swap_b32_e32 v68, v67
	s_waitcnt lgkmcnt(0)
	v_add_f32_e32 v67, v67, v68
	v_mov_b32_e32 v68, v67
	s_nop 1
	v_permlane32_swap_b32_e32 v68, v67
	s_and_saveexec_b64 s[66:67], s[38:39]
	s_cbranch_execz .LBB0_472
	v_lshl_add_u64 v[70:71], s[50:51], 0, v[64:65]
	s_lshr_b32 s76, s18, 3
	v_lshl_add_u64 v[70:71], v[70:71], 0, s[76:77]
	s_waitcnt lgkmcnt(0)
	v_add_f32_e32 v67, v67, v68
	global_store_dword v[70:71], v67, off

; __device__ __forceinline__ float dot4(const f32x4& v) { return (v[0] * v[0] + v[1] * v[1]) + (v[2] * v[2] + v[3] * v[3]); }
;     __device__ __forceinline__ void operator()(const f32x4 (&acc)[2][2][4][2], const Unit& u, int wr, int wc, int fr, int fq) const {
;     ...
;                         if (colw >= ZCQ && colw < ZKR) { float sb = dot4(v0) + dot4(v1); sb += __shfl_xor(sb, 16); sb += __shfl_xor(sb, 32);
;                             if (fq == 0) rstat[(size_t)row * 16 + ((colw - ZCQ) >> 5)] = sb; }
.LBB0_479:
	s_andn2_b64 vcc, exec, s[66:67]
	s_cbranch_vccnz .LBB0_483
	v_mul_f32_e32 v56, v53, v53
	v_mul_f32_e32 v57, v55, v55
	v_fmac_f32_e32 v56, v52, v52
	v_fmac_f32_e32 v57, v54, v54
	v_add_f32_e32 v56, v56, v57
	v_mul_f32_e32 v57, v49, v49
	v_mul_f32_e32 v58, v51, v51
	v_fmac_f32_e32 v57, v48, v48
	v_fmac_f32_e32 v58, v50, v50
	v_add_f32_e32 v57, v57, v58
	v_and_b32_e32 v58, 64, v215
	v_add_f32_e32 v56, v57, v56
	v_xor_b32_e32 v57, 16, v215
	v_add_u32_e32 v58, 64, v58
	v_cmp_lt_i32_e32 vcc, v57, v58
	s_nop 1
	v_cndmask_b32_e32 v57, v215, v57, vcc
	v_lshlrev_b32_e32 v57, 2, v57
	v_mov_b32_e32 v57, v56
	s_nop 1
	v_permlane16_swap_b32_e32 v57, v56
	s_waitcnt lgkmcnt(0)
	v_add_f32_e32 v56, v56, v57
	v_mov_b32_e32 v57, v56
	s_nop 1
	v_permlane32_swap_b32_e32 v57, v56
	s_and_saveexec_b64 s[66:67], s[38:39]
	s_cbranch_execz .LBB0_482
	v_lshl_add_u64 v[58:59], s[50:51], 0, v[64:65]
	s_lshr_b32 s76, s18, 3
	v_lshl_add_u64 v[58:59], v[58:59], 0, s[76:77]
	s_waitcnt lgkmcnt(0)
	v_add_f32_e32 v56, v56, v57
	global_store_dword v[58:59], v56, off

; __device__ __forceinline__ float dot4(const f32x4& v) { return (v[0] * v[0] + v[1] * v[1]) + (v[2] * v[2] + v[3] * v[3]); }
;     __device__ __forceinline__ void operator()(const f32x4 (&acc)[2][2][4][2], const Unit& u, int wr, int wc, int fr, int fq) const {
;     ...
;                         if (colw >= ZCQ && colw < ZKR) { float sb = dot4(v0) + dot4(v1); sb += __shfl_xor(sb, 16); sb += __shfl_xor(sb, 32);
;                             if (fq == 0) rstat[(size_t)row * 16 + ((colw - ZCQ) >> 5)] = sb; }
.LBB0_489:
	s_andn2_b64 vcc, exec, s[66:67]
	s_cbranch_vccnz .LBB0_493
	v_mul_f32_e32 v51, v45, v45
	v_mul_f32_e32 v52, v47, v47
	v_fmac_f32_e32 v51, v44, v44
	v_fmac_f32_e32 v52, v46, v46
	v_add_f32_e32 v51, v51, v52
	v_mul_f32_e32 v52, v41, v41
	v_mul_f32_e32 v53, v43, v43
	v_fmac_f32_e32 v52, v40, v40
	v_fmac_f32_e32 v53, v42, v42
	v_add_f32_e32 v52, v52, v53
	v_and_b32_e32 v53, 64, v215
	v_add_f32_e32 v51, v52, v51
	v_xor_b32_e32 v52, 16, v215
	v_add_u32_e32 v53, 64, v53
	v_cmp_lt_i32_e32 vcc, v52, v53
	s_nop 1
	v_cndmask_b32_e32 v52, v215, v52, vcc
	v_lshlrev_b32_e32 v52, 2, v52
	v_mov_b32_e32 v52, v51
	s_nop 1
	v_permlane16_swap_b32_e32 v52, v51
	s_waitcnt lgkmcnt(0)
	v_add_f32_e32 v51, v51, v52
	v_mov_b32_e32 v52, v51
	s_nop 1
	v_permlane32_swap_b32_e32 v52, v51
	s_and_saveexec_b64 s[66:67], s[38:39]
	s_cbranch_execz .LBB0_492
	v_lshl_add_u64 v[54:55], s[50:51], 0, v[48:49]
	s_lshr_b32 s76, s18, 3
	v_lshl_add_u64 v[54:55], v[54:55], 0, s[76:77]
	s_waitcnt lgkmcnt(0)
	v_add_f32_e32 v51, v51, v52
	global_store_dword v[54:55], v51, off

; __device__ __forceinline__ float dot4(const f32x4& v) { return (v[0] * v[0] + v[1] * v[1]) + (v[2] * v[2] + v[3] * v[3]); }
;     __device__ __forceinline__ void operator()(const f32x4 (&acc)[2][2][4][2], const Unit& u, int wr, int wc, int fr, int fq) const {
;     ...
;                         if (colw >= ZCQ && colw < ZKR) { float sb = dot4(v0) + dot4(v1); sb += __shfl_xor(sb, 16); sb += __shfl_xor(sb, 32);
;                             if (fq == 0) rstat[(size_t)row * 16 + ((colw - ZCQ) >> 5)] = sb; }
.LBB0_499:
	s_andn2_b64 vcc, exec, s[66:67]
	s_cbranch_vccnz .LBB0_503
	v_mul_f32_e32 v40, v37, v37
	v_mul_f32_e32 v41, v39, v39
	v_fmac_f32_e32 v40, v36, v36
	v_fmac_f32_e32 v41, v38, v38
	v_add_f32_e32 v40, v40, v41
	v_mul_f32_e32 v41, v33, v33
	v_mul_f32_e32 v42, v35, v35
	v_fmac_f32_e32 v41, v32, v32
	v_fmac_f32_e32 v42, v34, v34
	v_add_f32_e32 v41, v41, v42
	v_and_b32_e32 v42, 64, v215
	v_add_f32_e32 v40, v41, v40
	v_xor_b32_e32 v41, 16, v215
	v_add_u32_e32 v42, 64, v42
	v_cmp_lt_i32_e32 vcc, v41, v42
	s_nop 1
	v_cndmask_b32_e32 v41, v215, v41, vcc
	v_lshlrev_b32_e32 v41, 2, v41
	v_mov_b32_e32 v41, v40
	s_nop 1
	v_permlane16_swap_b32_e32 v41, v40
	s_waitcnt lgkmcnt(0)
	v_add_f32_e32 v40, v40, v41
	v_mov_b32_e32 v41, v40
	s_nop 1
	v_permlane32_swap_b32_e32 v41, v40
	s_and_saveexec_b64 s[66:67], s[38:39]
	s_cbranch_execz .LBB0_502
	v_lshl_add_u64 v[42:43], s[50:51], 0, v[48:49]
	s_lshr_b32 s76, s18, 3
	v_lshl_add_u64 v[42:43], v[42:43], 0, s[76:77]
	s_waitcnt lgkmcnt(0)
	v_add_f32_e32 v40, v40, v41
	global_store_dword v[42:43], v40, off

; __device__ __forceinline__ float dot4(const f32x4& v) { return (v[0] * v[0] + v[1] * v[1]) + (v[2] * v[2] + v[3] * v[3]); }
;     __device__ __forceinline__ void operator()(const f32x4 (&acc)[2][2][4][2], const Unit& u, int wr, int wc, int fr, int fq) const {
;     ...
;                         if (colw >= ZCQ && colw < ZKR) { float sb = dot4(v0) + dot4(v1); sb += __shfl_xor(sb, 16); sb += __shfl_xor(sb, 32);
;                             if (fq == 0) rstat[(size_t)row * 16 + ((colw - ZCQ) >> 5)] = sb; }
.LBB0_509:
	s_andn2_b64 vcc, exec, s[66:67]
	s_cbranch_vccnz .LBB0_513
	v_mul_f32_e32 v35, v29, v29
	v_mul_f32_e32 v36, v31, v31
	v_fmac_f32_e32 v35, v28, v28
	v_fmac_f32_e32 v36, v30, v30
	v_add_f32_e32 v35, v35, v36
	v_mul_f32_e32 v36, v25, v25
	v_mul_f32_e32 v37, v27, v27
	v_fmac_f32_e32 v36, v24, v24
	v_fmac_f32_e32 v37, v26, v26
	v_add_f32_e32 v36, v36, v37
	v_and_b32_e32 v37, 64, v215
	v_add_f32_e32 v35, v36, v35
	v_xor_b32_e32 v36, 16, v215
	v_add_u32_e32 v37, 64, v37
	v_cmp_lt_i32_e32 vcc, v36, v37
	s_nop 1
	v_cndmask_b32_e32 v36, v215, v36, vcc
	v_lshlrev_b32_e32 v36, 2, v36
	v_mov_b32_e32 v36, v35
	s_nop 1
	v_permlane16_swap_b32_e32 v36, v35
	s_waitcnt lgkmcnt(0)
	v_add_f32_e32 v35, v35, v36
	v_mov_b32_e32 v36, v35
	s_nop 1
	v_permlane32_swap_b32_e32 v36, v35
	s_and_saveexec_b64 s[66:67], s[38:39]
	s_cbranch_execz .LBB0_512
	v_lshl_add_u64 v[38:39], s[50:51], 0, v[32:33]
	s_lshr_b32 s76, s18, 3
	v_lshl_add_u64 v[38:39], v[38:39], 0, s[76:77]
	s_waitcnt lgkmcnt(0)
	v_add_f32_e32 v35, v35, v36
	global_store_dword v[38:39], v35, off

; __device__ __forceinline__ float dot4(const f32x4& v) { return (v[0] * v[0] + v[1] * v[1]) + (v[2] * v[2] + v[3] * v[3]); }
;     __device__ __forceinline__ void operator()(const f32x4 (&acc)[2][2][4][2], const Unit& u, int wr, int wc, int fr, int fq) const {
;     ...
;                         if (colw >= ZCQ && colw < ZKR) { float sb = dot4(v0) + dot4(v1); sb += __shfl_xor(sb, 16); sb += __shfl_xor(sb, 32);
;                             if (fq == 0) rstat[(size_t)row * 16 + ((colw - ZCQ) >> 5)] = sb; }
.LBB0_519:
	s_andn2_b64 vcc, exec, s[66:67]
	s_cbranch_vccnz .LBB0_523
	v_mul_f32_e32 v24, v21, v21
	v_mul_f32_e32 v25, v23, v23
	v_fmac_f32_e32 v24, v20, v20
	v_fmac_f32_e32 v25, v22, v22
	v_add_f32_e32 v24, v24, v25
	v_mul_f32_e32 v25, v17, v17
	v_mul_f32_e32 v26, v19, v19
	v_fmac_f32_e32 v25, v16, v16
	v_fmac_f32_e32 v26, v18, v18
	v_add_f32_e32 v25, v25, v26
	v_and_b32_e32 v26, 64, v215
	v_add_f32_e32 v24, v25, v24
	v_xor_b32_e32 v25, 16, v215
	v_add_u32_e32 v26, 64, v26
	v_cmp_lt_i32_e32 vcc, v25, v26
	s_nop 1
	v_cndmask_b32_e32 v25, v215, v25, vcc
	v_lshlrev_b32_e32 v25, 2, v25
	v_mov_b32_e32 v25, v24
	s_nop 1
	v_permlane16_swap_b32_e32 v25, v24
	s_waitcnt lgkmcnt(0)
	v_add_f32_e32 v24, v24, v25
	v_mov_b32_e32 v25, v24
	s_nop 1
	v_permlane32_swap_b32_e32 v25, v24
	s_and_saveexec_b64 s[66:67], s[38:39]
	s_cbranch_execz .LBB0_522
	v_lshl_add_u64 v[26:27], s[50:51], 0, v[32:33]
	s_lshr_b32 s76, s18, 3
	v_lshl_add_u64 v[26:27], v[26:27], 0, s[76:77]
	s_waitcnt lgkmcnt(0)
	v_add_f32_e32 v24, v24, v25
	global_store_dword v[26:27], v24, off

; __device__ __forceinline__ float dot4(const f32x4& v) { return (v[0] * v[0] + v[1] * v[1]) + (v[2] * v[2] + v[3] * v[3]); }
;     __device__ __forceinline__ void operator()(const f32x4 (&acc)[2][2][4][2], const Unit& u, int wr, int wc, int fr, int fq) const {
;     ...
;                         if (colw >= ZCQ && colw < ZKR) { float sb = dot4(v0) + dot4(v1); sb += __shfl_xor(sb, 16); sb += __shfl_xor(sb, 32);
;                             if (fq == 0) rstat[(size_t)row * 16 + ((colw - ZCQ) >> 5)] = sb; }
.LBB0_529:
	s_andn2_b64 vcc, exec, s[66:67]
	s_cbranch_vccnz .LBB0_533
	v_mul_f32_e32 v19, v13, v13
	v_mul_f32_e32 v20, v15, v15
	v_fmac_f32_e32 v19, v12, v12
	v_fmac_f32_e32 v20, v14, v14
	v_add_f32_e32 v19, v19, v20
	v_mul_f32_e32 v20, v9, v9
	v_mul_f32_e32 v21, v11, v11
	v_fmac_f32_e32 v20, v8, v8
	v_fmac_f32_e32 v21, v10, v10
	v_add_f32_e32 v20, v20, v21
	v_and_b32_e32 v21, 64, v215
	v_add_f32_e32 v19, v20, v19
	v_xor_b32_e32 v20, 16, v215
	v_add_u32_e32 v21, 64, v21
	v_cmp_lt_i32_e32 vcc, v20, v21
	s_nop 1
	v_cndmask_b32_e32 v20, v215, v20, vcc
	v_lshlrev_b32_e32 v20, 2, v20
	v_mov_b32_e32 v20, v19
	s_nop 1
	v_permlane16_swap_b32_e32 v20, v19
	s_waitcnt lgkmcnt(0)
	v_add_f32_e32 v19, v19, v20
	v_mov_b32_e32 v20, v19
	s_nop 1
	v_permlane32_swap_b32_e32 v20, v19
	s_and_saveexec_b64 s[66:67], s[38:39]
	s_cbranch_execz .LBB0_532
	v_lshl_add_u64 v[22:23], s[50:51], 0, v[16:17]
	s_lshr_b32 s76, s18, 3
	v_lshl_add_u64 v[22:23], v[22:23], 0, s[76:77]
	s_waitcnt lgkmcnt(0)
	v_add_f32_e32 v19, v19, v20
	global_store_dword v[22:23], v19, off

; __device__ __forceinline__ float dot4(const f32x4& v) { return (v[0] * v[0] + v[1] * v[1]) + (v[2] * v[2] + v[3] * v[3]); }
;     __device__ __forceinline__ void operator()(const f32x4 (&acc)[2][2][4][2], const Unit& u, int wr, int wc, int fr, int fq) const {
;     ...
;                         if (colw >= ZCQ && colw < ZKR) { float sb = dot4(v0) + dot4(v1); sb += __shfl_xor(sb, 16); sb += __shfl_xor(sb, 32);
;                             if (fq == 0) rstat[(size_t)row * 16 + ((colw - ZCQ) >> 5)] = sb; }
.LBB0_539:
	s_andn2_b64 vcc, exec, s[42:43]
	s_cbranch_vccnz .LBB0_543
	v_mul_f32_e32 v8, v5, v5
	v_mul_f32_e32 v9, v7, v7
	v_fmac_f32_e32 v8, v4, v4
	v_fmac_f32_e32 v9, v6, v6
	v_add_f32_e32 v8, v8, v9
	v_mul_f32_e32 v9, v1, v1
	v_mul_f32_e32 v10, v3, v3
	v_fmac_f32_e32 v9, v0, v0
	v_fmac_f32_e32 v10, v2, v2
	v_add_f32_e32 v9, v9, v10
	v_and_b32_e32 v10, 64, v215
	v_add_f32_e32 v8, v9, v8
	v_xor_b32_e32 v9, 16, v215
	v_add_u32_e32 v10, 64, v10
	v_cmp_lt_i32_e32 vcc, v9, v10
	s_nop 1
	v_cndmask_b32_e32 v9, v215, v9, vcc
	v_lshlrev_b32_e32 v9, 2, v9
	v_mov_b32_e32 v9, v8
	s_nop 1
	v_permlane16_swap_b32_e32 v9, v8
	s_waitcnt lgkmcnt(0)
	v_add_f32_e32 v8, v8, v9
	v_mov_b32_e32 v9, v8
	s_nop 1
	v_permlane32_swap_b32_e32 v9, v8
	s_and_saveexec_b64 s[42:43], s[38:39]
	s_cbranch_execz .LBB0_542
	v_lshl_add_u64 v[10:11], s[50:51], 0, v[16:17]
	s_lshr_b32 s76, s18, 3
	v_lshl_add_u64 v[10:11], v[10:11], 0, s[76:77]
	s_waitcnt lgkmcnt(0)
	v_add_f32_e32 v8, v8, v9
	global_store_dword v[10:11], v8, off
